# XCD grid barrier: non-leader workgroups poll the cross-XCD release generation directly (one forwarding hop less per barrier)
# speedup vs baseline: 1.0038x; 1.0029x over previous
.LBB0_806:
	s_or_b64 exec, exec, s[14:15]
	v_cvt_f32_u32_e32 v4, v2
	s_waitcnt vmcnt(0)
	v_readfirstlane_b32 s14, v3
	v_sub_u32_e32 v3, 0, v2
	v_rcp_iflag_f32_e32 v4, v4
	v_add_u32_e32 v5, s14, v1
	v_mul_f32_e32 v4, 0x4f7ffffe, v4
	v_cvt_u32_f32_e32 v4, v4
	v_mul_lo_u32 v1, v3, v4
	v_mul_hi_u32 v1, v4, v1
	v_add_u32_e32 v1, v4, v1
	v_mul_hi_u32 v1, v5, v1
	v_mul_lo_u32 v3, v1, v2
	v_sub_u32_e32 v3, v5, v3
	v_add_u32_e32 v4, 1, v1
	v_cmp_ge_u32_e32 vcc, v3, v2
	s_nop 1
	v_cndmask_b32_e32 v1, v1, v4, vcc
	v_sub_u32_e32 v4, v3, v2
	v_cndmask_b32_e32 v3, v3, v4, vcc
	v_add_u32_e32 v4, 1, v1
	v_cmp_ge_u32_e32 vcc, v3, v2
	v_add_u32_e32 v3, 1, v5
	s_nop 0
	v_cndmask_b32_e32 v1, v1, v4, vcc
	v_mul_lo_u32 v4, v2, v1
	v_add_u32_e32 v2, v4, v2
	v_cmp_ne_u32_e32 vcc, v3, v2
	s_and_saveexec_b64 s[14:15], vcc
	s_xor_b64 s[14:15], exec, s[14:15]
	s_cbranch_execz .LBB0_820
	v_readlane_b32 s16, v253, 62
	v_readlane_b32 s17, v253, 63
	s_waitcnt lgkmcnt(0)
	s_nop 3
	global_load_dword v0, v99, s[16:17] sc1
	s_waitcnt vmcnt(0)
	v_cmp_eq_u32_e32 vcc, v0, v1
	s_and_saveexec_b64 s[16:17], vcc
	s_cbranch_execz .LBB0_819
	s_mov_b32 s22, 1
	s_mov_b64 s[18:19], 0
	s_branch .LBB0_810

.LBB0_812:
	v_readlane_b32 s20, v253, 62
	v_readlane_b32 s21, v253, 63
	s_add_i32 s22, s22, 1
	s_mov_b64 s[44:45], -1
	s_nop 2
	global_load_dword v0, v99, s[20:21] sc1
	s_waitcnt vmcnt(0)
	v_cmp_ne_u32_e32 vcc, v0, v1
	s_orn2_b64 s[42:43], vcc, exec
	s_branch .LBB0_809

.LBB0_1018:
	s_or_b64 exec, exec, s[6:7]
	v_cvt_f32_u32_e32 v4, v2
	s_waitcnt vmcnt(0)
	v_readfirstlane_b32 s6, v3
	v_sub_u32_e32 v3, 0, v2
	v_rcp_iflag_f32_e32 v4, v4
	v_add_u32_e32 v5, s6, v1
	v_mul_f32_e32 v4, 0x4f7ffffe, v4
	v_cvt_u32_f32_e32 v4, v4
	v_mul_lo_u32 v1, v3, v4
	v_mul_hi_u32 v1, v4, v1
	v_add_u32_e32 v1, v4, v1
	v_mul_hi_u32 v1, v5, v1
	v_mul_lo_u32 v3, v1, v2
	v_sub_u32_e32 v3, v5, v3
	v_add_u32_e32 v4, 1, v1
	v_cmp_ge_u32_e32 vcc, v3, v2
	s_nop 1
	v_cndmask_b32_e32 v1, v1, v4, vcc
	v_sub_u32_e32 v4, v3, v2
	v_cndmask_b32_e32 v3, v3, v4, vcc
	v_add_u32_e32 v4, 1, v1
	v_cmp_ge_u32_e32 vcc, v3, v2
	v_add_u32_e32 v3, 1, v5
	s_nop 0
	v_cndmask_b32_e32 v1, v1, v4, vcc
	v_mul_lo_u32 v4, v2, v1
	v_add_u32_e32 v2, v4, v2
	v_cmp_ne_u32_e32 vcc, v3, v2
	s_and_saveexec_b64 s[6:7], vcc
	s_xor_b64 s[6:7], exec, s[6:7]
	s_cbranch_execz .LBB0_1032
	v_readlane_b32 s8, v253, 62
	v_readlane_b32 s9, v253, 63
	s_waitcnt lgkmcnt(0)
	s_nop 3
	global_load_dword v0, v99, s[8:9] sc1
	s_waitcnt vmcnt(0)
	v_cmp_eq_u32_e32 vcc, v0, v1
	s_and_saveexec_b64 s[8:9], vcc
	s_cbranch_execz .LBB0_1031
	s_mov_b32 s22, 1
	s_mov_b64 s[10:11], 0
	s_branch .LBB0_1022

.LBB0_1024:
	v_readlane_b32 s14, v253, 62
	v_readlane_b32 s15, v253, 63
	s_add_i32 s22, s22, 1
	s_mov_b64 s[16:17], -1
	s_nop 2
	global_load_dword v0, v99, s[14:15] sc1
	s_waitcnt vmcnt(0)
	v_cmp_ne_u32_e32 vcc, v0, v1
	s_orn2_b64 s[14:15], vcc, exec
	s_branch .LBB0_1021

.LBB0_1370:
	s_or_b64 exec, exec, s[6:7]
	v_cvt_f32_u32_e32 v4, v2
	s_waitcnt vmcnt(0)
	v_readfirstlane_b32 s6, v3
	v_sub_u32_e32 v3, 0, v2
	v_rcp_iflag_f32_e32 v4, v4
	v_add_u32_e32 v5, s6, v1
	v_mul_f32_e32 v4, 0x4f7ffffe, v4
	v_cvt_u32_f32_e32 v4, v4
	v_mul_lo_u32 v1, v3, v4
	v_mul_hi_u32 v1, v4, v1
	v_add_u32_e32 v1, v4, v1
	v_mul_hi_u32 v1, v5, v1
	v_mul_lo_u32 v3, v1, v2
	v_sub_u32_e32 v3, v5, v3
	v_add_u32_e32 v4, 1, v1
	v_cmp_ge_u32_e32 vcc, v3, v2
	s_nop 1
	v_cndmask_b32_e32 v1, v1, v4, vcc
	v_sub_u32_e32 v4, v3, v2
	v_cndmask_b32_e32 v3, v3, v4, vcc
	v_add_u32_e32 v4, 1, v1
	v_cmp_ge_u32_e32 vcc, v3, v2
	v_add_u32_e32 v3, 1, v5
	s_nop 0
	v_cndmask_b32_e32 v1, v1, v4, vcc
	v_mul_lo_u32 v4, v2, v1
	v_add_u32_e32 v2, v4, v2
	v_cmp_ne_u32_e32 vcc, v3, v2
	s_and_saveexec_b64 s[6:7], vcc
	s_xor_b64 s[6:7], exec, s[6:7]
	s_cbranch_execz .LBB0_1384
	v_readlane_b32 s8, v253, 62
	v_readlane_b32 s9, v253, 63
	s_waitcnt lgkmcnt(0)
	s_nop 3
	global_load_dword v0, v99, s[8:9] sc1
	s_waitcnt vmcnt(0)
	v_cmp_eq_u32_e32 vcc, v0, v1
	s_and_saveexec_b64 s[8:9], vcc
	s_cbranch_execz .LBB0_1383
	s_mov_b32 s24, 1
	s_mov_b64 s[10:11], 0
	s_branch .LBB0_1374

.LBB0_1376:
	v_readlane_b32 s14, v253, 62
	v_readlane_b32 s15, v253, 63
	s_add_i32 s24, s24, 1
	s_mov_b64 s[16:17], -1
	s_nop 2
	global_load_dword v0, v99, s[14:15] sc1
	s_waitcnt vmcnt(0)
	v_cmp_ne_u32_e32 vcc, v0, v1
	s_orn2_b64 s[14:15], vcc, exec
	s_branch .LBB0_1373
